# attention transform: lane^32 exchanges via v_permlane32_swap instead of ds_bpermute round trips (same values)
# baseline (speedup 1.0000x reference)
; __device__ __forceinline__ float fast_exp2(float x) { return __builtin_amdgcn_exp2f(x); }
; __device__ __forceinline__ float fast_rcp(float x) { return __builtin_amdgcn_rcpf(x); }
; template <int NB, bool MASK> __device__ __forceinline__ void sb_transform(f32x16* P, float& R, int hi, int kpos0, int qpos) {
;     float T[NB][4];
; #pragma unroll
;     for (int b = 0; b < NB; ++b)
; #pragma unroll
;         for (int g = 0; g < 4; ++g) {
;             float be[4], f[4];
; #pragma unroll
;             for (int i = 0; i < 4; ++i) {
;                 const float z = fmaxf(P[b][4 * g + i], -100.f);
;                 const float e = fast_exp2(-z), rc = fast_rcp(1.f + e);
;                 be[i] = rc; f[i] = e * rc;
;                 if (MASK) { const bool ok = (kpos0 + 32 * b + 8 * g + 4 * hi + i) < qpos; be[i] = ok ? be[i] : 0.f; f[i] = ok ? f[i] : 1.f; }
;             }
.LBB0_872:
	s_lshl_b32 s87, s86, 14
	v_add_u32_e32 v2, s87, v211
	v_add_u32_e32 v172, v2, v212
	ds_read_b128 v[176:179], v172 offset:40960
	v_add_u32_e32 v174, v2, v213
	ds_read_b128 v[180:183], v174 offset:40960
	v_add_u32_e32 v175, v2, v214
	s_or_b32 s11, s10, 63
	s_cmp_ge_i32 s11, s78
	s_mov_b64 s[8:9], -1
	s_cselect_b64 s[50:51], -1, 0
	s_cmp_lt_i32 s11, s78
	s_waitcnt lgkmcnt(1)
	v_mfma_f32_32x32x16_bf16 v[84:99], v[176:179], v[100:103], v[68:83]
	v_add_u32_e32 v176, v2, v215
	v_add_u32_e32 v177, v2, v216
	s_waitcnt lgkmcnt(0)
	v_mfma_f32_32x32x16_bf16 v[84:99], v[180:183], v[104:107], v[84:99]
	ds_read_b128 v[178:181], v175 offset:40960
	ds_read_b128 v[182:185], v176 offset:40960
	s_waitcnt lgkmcnt(1)
	v_mfma_f32_32x32x16_bf16 v[84:99], v[178:181], v[108:111], v[84:99]
	v_add_u32_e32 v178, v2, v217
	v_add_u32_e32 v179, v2, v218
	s_waitcnt lgkmcnt(0)
	v_mfma_f32_32x32x16_bf16 v[84:99], v[182:185], v[112:115], v[84:99]
	ds_read_b128 v[180:183], v177 offset:40960
	ds_read_b128 v[184:187], v178 offset:40960
	s_waitcnt lgkmcnt(1)
	v_mfma_f32_32x32x16_bf16 v[84:99], v[180:183], v[116:119], v[84:99]
	v_add_u32_e32 v180, v2, v219
	v_or_b32_e32 v2, s10, v210
	s_waitcnt lgkmcnt(0)
	v_mfma_f32_32x32x16_bf16 v[84:99], v[184:187], v[120:123], v[84:99]
	ds_read_b128 v[182:185], v179 offset:40960
	ds_read_b128 v[186:189], v180 offset:40960
	s_waitcnt lgkmcnt(1)
	v_mfma_f32_32x32x16_bf16 v[84:99], v[182:185], v[124:127], v[84:99]
	s_waitcnt lgkmcnt(0)
	v_mfma_f32_32x32x16_bf16 v[84:99], v[186:189], v[128:131], v[84:99]
	s_nop 11
	v_max_f32_e64 v227, -v84, -v84
	v_max_f32_e64 v226, -v85, -v85
	v_max_f32_e64 v225, -v86, -v86
	v_max_f32_e64 v224, -v87, -v87
	v_max_f32_e64 v223, -v88, -v88
	v_max_f32_e64 v222, -v89, -v89
	v_max_f32_e64 v221, -v90, -v90
	v_max_f32_e64 v189, -v91, -v91
	v_max_f32_e64 v188, -v92, -v92
	v_max_f32_e64 v187, -v93, -v93
	v_max_f32_e64 v186, -v94, -v94
	v_max_f32_e64 v185, -v95, -v95
	v_max_f32_e64 v183, -v96, -v96
	v_max_f32_e64 v184, -v97, -v97
	v_max_f32_e64 v182, -v98, -v98
	v_max_f32_e64 v181, -v99, -v99
	s_cbranch_scc1 .LBB0_874
	v_min_f32_e32 v84, 0x42c80000, v227
	v_exp_f32_e32 v84, v84
	v_min_f32_e32 v85, 0x42c80000, v226
	v_exp_f32_e32 v85, v85
	v_or_b32_e32 v87, 32, v2
	v_add_f32_e32 v86, 1.0, v84
	v_rcp_f32_e32 v86, v86
	v_add_f32_e32 v88, 1.0, v85
	v_rcp_f32_e32 v88, v88
	v_min_f32_e32 v90, 0x42c80000, v224
	v_mul_f32_e32 v89, v84, v86
	v_cmp_lt_i32_e32 vcc, v87, v168
	v_exp_f32_e32 v90, v90
	v_mul_f32_e32 v87, v85, v88
	v_cndmask_b32_e32 v84, 0, v86, vcc
	v_cndmask_b32_e32 v86, 1.0, v89, vcc
	v_or_b32_e32 v89, 33, v2
	v_mov_b32_e32 v85, s45
	v_cmp_lt_i32_e32 vcc, v89, v168
	v_min_f32_e32 v91, 0x42c80000, v223
	v_exp_f32_e32 v93, v91
	v_cndmask_b32_e32 v85, v85, v88, vcc
	v_min_f32_e32 v88, 0x42c80000, v225
	v_exp_f32_e32 v92, v88
	v_add_f32_e32 v88, 1.0, v90
	v_rcp_f32_e32 v89, v88
	v_min_f32_e32 v91, 0x42c80000, v222
	v_exp_f32_e32 v91, v91
	v_cndmask_b32_e32 v88, 1.0, v87, vcc
	v_add_f32_e32 v87, 1.0, v92
	v_rcp_f32_e32 v96, v87
	v_mul_f32_e32 v87, v90, v89
	v_or_b32_e32 v90, 35, v2
	v_cmp_lt_i32_e32 vcc, v90, v168
	v_add_f32_e32 v90, 1.0, v91
	v_rcp_f32_e32 v95, v90
	v_min_f32_e32 v90, 0x42c80000, v221
	v_exp_f32_e32 v90, v90
	v_cndmask_b32_e32 v94, 1.0, v87, vcc
	v_add_f32_e32 v87, 1.0, v93
	v_rcp_f32_e32 v97, v87
	v_add_f32_e32 v98, 1.0, v90
	v_rcp_f32_e32 v99, v98
	v_min_f32_e32 v98, 0x42c80000, v189
	v_exp_f32_e32 v98, v98
	v_mul_f32_e32 v87, v91, v95
	v_or_b32_e32 v91, 41, v2
	v_cmp_lt_i32_e64 s[8:9], v91, v168
	v_min_f32_e32 v91, 0x42c80000, v188
	v_exp_f32_e32 v91, v91
	v_cndmask_b32_e64 v173, 1.0, v87, s[8:9]
	v_mul_f32_e32 v87, v90, v99
	v_add_f32_e32 v90, 1.0, v98
	v_rcp_f32_e32 v231, v90
	v_or_b32_e32 v90, 42, v2
	v_cmp_lt_i32_e64 s[10:11], v90, v168
	v_or_b32_e32 v90, 43, v2
	v_cmp_lt_i32_e64 s[12:13], v90, v168
	v_cndmask_b32_e64 v248, 1.0, v87, s[10:11]
	v_mul_f32_e32 v87, v98, v231
	v_cndmask_b32_e64 v249, 1.0, v87, s[12:13]
	v_min_f32_e32 v87, 0x42c80000, v187
	v_add_f32_e32 v90, 1.0, v91
	v_exp_f32_e32 v87, v87
	v_rcp_f32_e32 v242, v90
	v_or_b32_e32 v90, 48, v2
	v_cmp_lt_i32_e64 s[14:15], v90, v168
	v_add_f32_e32 v98, 1.0, v87
	v_mul_f32_e32 v91, v91, v242
	v_min_f32_e32 v90, 0x42c80000, v185
	v_min_f32_e32 v230, 0x42c80000, v184
	v_rcp_f32_e32 v243, v98
	v_cndmask_b32_e64 v98, 1.0, v91, s[14:15]
	v_exp_f32_e32 v91, v90
	v_exp_f32_e32 v232, v230
	v_min_f32_e32 v90, 0x42c80000, v186
	v_or_b32_e32 v229, 51, v2
	v_exp_f32_e32 v90, v90
	v_add_f32_e32 v228, 1.0, v91
	v_cmp_lt_i32_e64 s[20:21], v229, v168
	v_add_f32_e32 v229, 1.0, v232
	v_rcp_f32_e32 v244, v228
	v_rcp_f32_e32 v245, v229
	v_min_f32_e32 v229, 0x42c80000, v182
	v_or_b32_e32 v170, 49, v2
	v_exp_f32_e32 v233, v229
	v_mul_f32_e32 v87, v87, v243
	v_cmp_lt_i32_e64 s[16:17], v170, v168
	v_pk_mul_f32 v[92:93], v[92:93], v[96:97]
	v_add_f32_e32 v234, 1.0, v233
	v_cndmask_b32_e64 v170, 1.0, v87, s[16:17]
	v_add_f32_e32 v87, 1.0, v90
	v_rcp_f32_e32 v228, v87
	v_mul_f32_e32 v87, v91, v244
	v_min_f32_e32 v91, 0x42c80000, v183
	v_exp_f32_e32 v91, v91
	v_rcp_f32_e32 v246, v234
	v_min_f32_e32 v234, 0x42c80000, v181
	v_exp_f32_e32 v234, v234
	v_cndmask_b32_e64 v230, 1.0, v87, s[20:21]
	v_add_f32_e32 v87, 1.0, v91
	v_rcp_f32_e32 v229, v87
	v_mul_f32_e32 v87, v232, v245
	v_or_b32_e32 v232, 57, v2
	v_cmp_lt_i32_e64 s[26:27], v232, v168
	v_add_f32_e32 v232, 1.0, v234
	v_rcp_f32_e32 v250, v232
	v_or_b32_e32 v232, 58, v2
	v_cndmask_b32_e64 v247, 1.0, v87, s[26:27]
	v_mul_f32_e32 v87, v233, v246
	v_cmp_lt_i32_e64 s[22:23], v232, v168
	v_or_b32_e32 v232, 59, v2
	v_cmp_lt_i32_e64 s[18:19], v232, v168
	v_cndmask_b32_e64 v251, 1.0, v87, s[22:23]
; __device__ __forceinline__ float fast_exp2(float x) { return __builtin_amdgcn_exp2f(x); }
; __device__ __forceinline__ float fast_rcp(float x) { return __builtin_amdgcn_rcpf(x); }
; template <int NB, bool MASK> __device__ __forceinline__ void sb_transform(f32x16* P, float& R, int hi, int kpos0, int qpos) {
;     float T[NB][4];
; #pragma unroll
;     for (int b = 0; b < NB; ++b)
; #pragma unroll
;         for (int g = 0; g < 4; ++g) {
;             float be[4], f[4];
; #pragma unroll
;             for (int i = 0; i < 4; ++i) {
;                 const float z = fmaxf(P[b][4 * g + i], -100.f);
;                 const float e = fast_exp2(-z), rc = fast_rcp(1.f + e);
;                 be[i] = rc; f[i] = e * rc;
;                 if (MASK) { const bool ok = (kpos0 + 32 * b + 8 * g + 4 * hi + i) < qpos; be[i] = ok ? be[i] : 0.f; f[i] = ok ? f[i] : 1.f; }
;             }
;             const float e2 = f[3], e1 = f[2] * f[3], e0 = f[1] * e1;
;             T[b][g] = f[0] * e0;
;             P[b][4 * g + 0] = be[0] * e0; P[b][4 * g + 1] = be[1] * e1; P[b][4 * g + 2] = be[2] * e2; P[b][4 * g + 3] = be[3];
;         }
;     float E = R;
; #pragma unroll
;     for (int b = NB - 1; b >= 0; --b)
; #pragma unroll
;         for (int g = 3; g >= 0; --g) {
;             const float To = __shfl_xor(T[b][g], 32);
;             const float Eg = hi ? E : E * To;
; #pragma unroll
;             for (int i = 0; i < 4; ++i) P[b][4 * g + i] *= Eg;
;             E = E * T[b][g] * To;
;         }
;     R = E;
; }
	v_mul_f32_e32 v87, v234, v250
	v_cndmask_b32_e64 v252, 1.0, v87, s[18:19]
	v_xor_b32_e32 v87, 32, v191
	v_add_u32_e32 v232, 64, v192
	v_cmp_lt_i32_e64 s[28:29], v87, v232
	v_or_b32_e32 v232, 50, v2
	v_pk_mul_f32 v[90:91], v[90:91], v[228:229]
	v_cndmask_b32_e64 v87, v191, v87, s[28:29]
	v_lshlrev_b32_e32 v253, 2, v87
	v_or_b32_e32 v87, 56, v2
	v_cmp_lt_i32_e64 s[28:29], v87, v1
	v_or_b32_e32 v87, 34, v2
	v_cmp_lt_i32_e64 s[30:31], v232, v168
	v_cmp_lt_i32_e64 s[34:35], v87, v168
	v_cndmask_b32_e64 v233, 1.0, v91, s[28:29]
	v_cndmask_b32_e64 v232, 1.0, v90, s[30:31]
	v_cndmask_b32_e64 v90, 0, v96, s[34:35]
	v_or_b32_e32 v91, 40, v2
	v_mov_b32_e32 v87, s45
	v_mul_f32_e32 v234, v94, v90
	v_mov_b32_e32 v90, s45
	v_cndmask_b32_e32 v235, v87, v89, vcc
	v_cmp_lt_i32_e32 vcc, v91, v1
	v_cndmask_b32_e64 v90, v90, v99, s[10:11]
	v_mul_f32_e32 v91, v251, v252
	v_cndmask_b32_e64 v241, v87, v231, s[12:13]
	v_mul_f32_e32 v240, v249, v90
	v_mov_b32_e32 v90, s45
	v_mul_f32_e32 v231, v247, v91
	v_cndmask_b32_e64 v236, 1.0, v92, s[34:35]
	v_cndmask_b32_e64 v96, v90, v242, s[14:15]
	v_cndmask_b32_e64 v90, 0, v228, s[30:31]
	v_cndmask_b32_e64 v92, 0, v229, s[28:29]
	v_pk_mul_f32 v[228:229], v[232:233], v[230:231]
	v_mov_b32_e32 v99, v229
	v_mov_b32_e32 v255, v229
	s_nop 1
	v_permlane32_swap_b32_e32 v99, v255
	v_cndmask_b32_e64 v99, v99, v255, s[6:7]
	v_pk_mul_f32 v[232:233], v[170:171], v[228:229]
	v_cndmask_b32_e32 v237, 1.0, v93, vcc
	v_cndmask_b32_e32 v238, 0, v97, vcc
	v_cndmask_b32_e64 v97, v87, v243, s[16:17]
	v_cndmask_b32_e64 v243, v87, v244, s[20:21]
	v_cndmask_b32_e64 v93, v87, v245, s[26:27]
	s_waitcnt lgkmcnt(0)
	v_pk_mul_f32 v[244:245], v[98:99], v[232:233]
	v_mov_b32_e32 v89, v244
	v_mov_b32_e32 v255, v244
	s_nop 1
	v_permlane32_swap_b32_e32 v89, v255
	v_cndmask_b32_e64 v89, v89, v255, s[6:7]
	v_cndmask_b32_e64 v239, v87, v95, s[8:9]
	v_mul_f32_e32 v242, v230, v90
	v_mov_b32_e32 v90, s45
	v_cndmask_b32_e64 v247, v87, v250, s[18:19]
	v_mul_f32_e32 v87, v171, v99
	v_mul_f32_e32 v229, v248, v249
	v_cndmask_b32_e64 v90, v90, v246, s[22:23]
	v_cndmask_b32_e64 v98, v171, v87, s[6:7]
	s_waitcnt lgkmcnt(0)
	v_mul_f32_e32 v87, v245, v89
	v_mul_f32_e32 v95, v173, v229
	v_mul_f32_e32 v246, v252, v90
	v_cndmask_b32_e64 v170, v245, v87, s[6:7]
	v_mul_f32_e32 v87, v244, v245
	v_mov_b32_e32 v90, v231
	v_pk_mul_f32 v[230:231], v[236:237], v[94:95]
	v_mul_f32_e32 v89, v87, v89
	v_mov_b32_e32 v87, v231
	v_mov_b32_e32 v255, v231
	s_nop 1
	v_permlane32_swap_b32_e32 v87, v255
	v_cndmask_b32_e64 v87, v87, v255, s[6:7]
	v_mov_b32_e32 v233, v228
	v_pk_mul_f32 v[96:97], v[232:233], v[96:97]
	v_pk_mul_f32 v[232:233], v[88:89], v[230:231]
	v_mov_b32_e32 v228, v95
	v_pk_mul_f32 v[90:91], v[90:91], v[92:93]
	v_pk_mul_f32 v[94:95], v[228:229], v[238:239]
	s_waitcnt lgkmcnt(0)
	v_pk_mul_f32 v[228:229], v[86:87], v[232:233]
	v_pk_mul_f32 v[90:91], v[90:91], v[98:99] op_sel_hi:[1,0]
	v_pk_mul_f32 v[92:93], v[246:247], v[98:99] op_sel_hi:[1,0]
	v_pk_mul_f32 v[96:97], v[96:97], v[170:171] op_sel_hi:[1,0]
	v_pk_mul_f32 v[98:99], v[242:243], v[170:171] op_sel_hi:[1,0]
	v_mov_b32_e32 v170, v228
	v_mov_b32_e32 v255, v228
	s_nop 1
	v_permlane32_swap_b32_e32 v170, v255
	v_cndmask_b32_e64 v170, v170, v255, s[6:7]
	v_mul_f32_e32 v86, v89, v87
	v_cndmask_b32_e64 v86, v89, v86, s[6:7]
	v_pk_mul_f32 v[88:89], v[94:95], v[86:87] op_sel_hi:[1,0]
	v_mov_b32_e32 v233, v230
	s_waitcnt lgkmcnt(0)
	v_mul_f32_e32 v94, v229, v170
	v_cndmask_b32_e64 v94, v229, v94, s[6:7]
	v_pk_mul_f32 v[84:85], v[232:233], v[84:85]
	v_mul_f32_e32 v173, v228, v229
	v_pk_mul_f32 v[86:87], v[240:241], v[86:87] op_sel_hi:[1,0]
	v_pk_mul_f32 v[84:85], v[84:85], v[94:95] op_sel_hi:[1,0]
	v_pk_mul_f32 v[94:95], v[234:235], v[94:95] op_sel_hi:[1,0]
	v_mul_f32_e32 v173, v173, v170
	s_mov_b64 s[8:9], 0
.LBB0_874:
	s_andn2_b64 vcc, exec, s[8:9]
	s_cbranch_vccnz .LBB0_876
	v_min_f32_e32 v84, 0x42c80000, v227
	v_exp_f32_e32 v85, v84
	v_min_f32_e32 v84, 0x42c80000, v226
	v_exp_f32_e32 v84, v84
	v_min_f32_e32 v86, 0x42c80000, v225
	v_add_f32_e32 v87, 1.0, v85
	v_rcp_f32_e32 v94, v87
	v_min_f32_e32 v87, 0x42c80000, v224
	v_exp_f32_e32 v86, v86
	v_add_f32_e32 v89, 1.0, v84
	v_exp_f32_e32 v224, v87
	v_min_f32_e32 v87, 0x42c80000, v223
	v_rcp_f32_e32 v170, v89
	v_exp_f32_e32 v87, v87
	v_min_f32_e32 v89, 0x42c80000, v222
	v_exp_f32_e32 v89, v89
	v_min_f32_e32 v90, 0x42c80000, v221
	v_mul_f32_e32 v88, v85, v94
	v_add_f32_e32 v85, 1.0, v86
	v_exp_f32_e32 v90, v90
	v_min_f32_e32 v91, 0x42c80000, v189
	v_rcp_f32_e32 v226, v85
	v_add_f32_e32 v85, 1.0, v224
	v_exp_f32_e32 v91, v91
	v_rcp_f32_e32 v222, v85
	v_add_f32_e32 v85, 1.0, v87
	v_rcp_f32_e32 v227, v85
	v_add_f32_e32 v85, 1.0, v89
	v_rcp_f32_e32 v189, v85
	v_add_f32_e32 v85, 1.0, v90
	v_rcp_f32_e32 v228, v85
	v_add_f32_e32 v85, 1.0, v91
	v_rcp_f32_e32 v229, v85
	v_min_f32_e32 v85, 0x42c80000, v188
	v_exp_f32_e32 v85, v85
	v_mul_f32_e32 v225, v89, v189
	v_pk_mul_f32 v[90:91], v[90:91], v[228:229]
	v_pk_mul_f32 v[86:87], v[86:87], v[226:227]
	v_pk_mul_f32 v[230:231], v[90:91], v[90:91] op_sel:[0,1] op_sel_hi:[1,0]
	v_min_f32_e32 v90, 0x42c80000, v186
	v_mul_f32_e32 v228, v228, v91
	v_exp_f32_e32 v90, v90
	v_min_f32_e32 v91, 0x42c80000, v185
	v_exp_f32_e32 v91, v91
	v_add_f32_e32 v89, 1.0, v85
	v_rcp_f32_e32 v96, v89
	v_min_f32_e32 v89, 0x42c80000, v187
	v_exp_f32_e32 v92, v89
	v_add_f32_e32 v89, 1.0, v90
	v_rcp_f32_e32 v98, v89
	v_add_f32_e32 v89, 1.0, v91
	v_rcp_f32_e32 v99, v89
	v_mul_f32_e32 v186, v85, v96
	v_add_f32_e32 v85, 1.0, v92
	v_rcp_f32_e32 v232, v85
	v_pk_mul_f32 v[90:91], v[90:91], v[98:99]
	v_min_f32_e32 v85, 0x42c80000, v184
	v_pk_mul_f32 v[184:185], v[90:91], v[90:91] op_sel:[0,1] op_sel_hi:[1,0]
	v_min_f32_e32 v90, 0x42c80000, v182
	v_exp_f32_e32 v182, v90
	v_min_f32_e32 v90, 0x42c80000, v181
	v_min_f32_e32 v89, 0x42c80000, v183
	v_exp_f32_e32 v183, v90
	v_exp_f32_e32 v85, v85
	v_exp_f32_e32 v234, v89
	v_add_f32_e32 v90, 1.0, v182
	v_rcp_f32_e32 v236, v90
	v_add_f32_e32 v90, 1.0, v183
	v_rcp_f32_e32 v237, v90
	v_add_f32_e32 v89, 1.0, v85
	v_rcp_f32_e32 v89, v89
	v_add_f32_e32 v90, 1.0, v234
	v_rcp_f32_e32 v238, v90
	v_pk_mul_f32 v[182:183], v[182:183], v[236:237]
	v_mul_f32_e32 v235, v85, v89
	v_pk_mul_f32 v[240:241], v[182:183], v[182:183] op_sel:[0,1] op_sel_hi:[1,0]
	v_xor_b32_e32 v85, 32, v191
	v_mov_b32_e32 v239, v240
	v_add_u32_e32 v90, 64, v192
	v_pk_mul_f32 v[234:235], v[234:235], v[238:239]
	v_cmp_lt_i32_e32 vcc, v85, v90
	v_mov_b32_e32 v93, v234
	v_mov_b32_e32 v233, v235
	v_cndmask_b32_e32 v85, v191, v85, vcc
	v_lshlrev_b32_e32 v95, 2, v85
	v_pk_mul_f32 v[92:93], v[92:93], v[232:233]
	v_mov_b32_e32 v187, v93
	v_mov_b32_e32 v255, v93
	s_nop 1
	v_permlane32_swap_b32_e32 v187, v255
	v_cndmask_b32_e64 v187, v187, v255, s[6:7]
	v_mov_b32_e32 v185, v171
	v_mul_f32_e32 v236, v236, v183
	v_pk_mul_f32 v[182:183], v[184:185], v[92:93]
	v_mov_b32_e32 v223, v230
	s_waitcnt lgkmcnt(0)
; #define SBAR() __builtin_amdgcn_sched_barrier(0)
; template <int D0, int KS0> __device__ __forceinline__ void pv_one(f32x16& od, int vb, const bf16x8* pa) {
;     const s16x4 l0 = tr_read<v_rd_off(D0, KS0, 0)>(vb), h0 = tr_read<v_rd_off(D0, KS0, 1)>(vb), l1 = tr_read<v_rd_off(D0, KS0 + 1, 0)>(vb), h1 = tr_read<v_rd_off(D0, KS0 + 1, 1)>(vb);
;     asm volatile("s_waitcnt lgkmcnt(0)" ::: "memory"); SBAR();
;     od = __builtin_amdgcn_mfma_f32_32x32x16_bf16(pa[0], PKV(l0, h0), od, 0, 0, 0);
;     od = __builtin_amdgcn_mfma_f32_32x32x16_bf16(pa[1], PKV(l1, h1), od, 0, 0, 0);
; }
; template <int KS0> __device__ __forceinline__ void pv_blk(f32x16* o, int vb, const bf16x8* pa) {
;     pv_one<0, KS0>(o[0], vb, pa); pv_one<1, KS0>(o[1], vb, pa); pv_one<2, KS0>(o[2], vb, pa); pv_one<3, KS0>(o[3], vb, pa);
; }
; __device__ __forceinline__ void pack_p(const f32x16& P, bf16x8& out0, bf16x8& out1) {
;     ...
;     PK4(0, out0); PK4(8, out1);
;     ...
; }
; template <int MODE> ...
;     ...
;             ATT_BLOCK(1);
;             ATT_BLOCK(0);
	v_mul_f32_e32 v85, v171, v187
	v_pk_mul_f32 v[186:187], v[182:183], v[186:187]
	v_cndmask_b32_e64 v92, v171, v85, s[6:7]
	v_mov_b32_e32 v171, v186
	v_mov_b32_e32 v255, v186
	s_nop 1
	v_permlane32_swap_b32_e32 v171, v255
	v_cndmask_b32_e64 v171, v171, v255, s[6:7]
	v_mov_b32_e32 v97, v232
	v_mov_b32_e32 v183, v184
	v_pk_mul_f32 v[184:185], v[224:225], v[222:223]
	v_pk_mul_f32 v[96:97], v[96:97], v[182:183]
	s_waitcnt lgkmcnt(0)
	v_mul_f32_e32 v85, v187, v171
	v_cndmask_b32_e64 v188, v187, v85, s[6:7]
	v_pk_mul_f32 v[182:183], v[186:187], v[186:187] op_sel_hi:[0,1]
	v_pk_mul_f32 v[186:187], v[86:87], v[184:185]
	v_mov_b32_e32 v239, v89
	v_mov_b32_e32 v89, v187
	v_mov_b32_e32 v255, v187
	s_nop 1
	v_permlane32_swap_b32_e32 v89, v255
	v_cndmask_b32_e64 v89, v89, v255, s[6:7]
	v_mov_b32_e32 v85, v183
	v_pk_mul_f32 v[84:85], v[84:85], v[170:171]
	v_mul_f32_e32 v98, v98, v91
	v_pk_mul_f32 v[182:183], v[186:187], v[84:85]
	v_pk_mul_f32 v[96:97], v[96:97], v[188:189] op_sel_hi:[1,0]
	v_pk_mul_f32 v[98:99], v[98:99], v[188:189] op_sel_hi:[1,0]
	v_mul_f32_e32 v224, v226, v184
	v_mov_b32_e32 v188, v227
	s_waitcnt lgkmcnt(0)
	v_pk_mul_f32 v[226:227], v[182:183], v[88:89]
	v_mov_b32_e32 v171, v226
	v_mov_b32_e32 v255, v226
	s_nop 1
	v_permlane32_swap_b32_e32 v171, v255
	v_cndmask_b32_e64 v171, v171, v255, s[6:7]
	v_mul_f32_e32 v84, v85, v89
	v_pk_mov_b32 v[86:87], v[184:185], v[230:231] op_sel:[1,0]
	v_cndmask_b32_e64 v84, v85, v84, s[6:7]
	v_pk_mul_f32 v[86:87], v[188:189], v[86:87]
	v_pk_mov_b32 v[90:91], v[234:235], v[240:241] op_sel:[1,0]
	v_pk_mul_f32 v[88:89], v[86:87], v[84:85] op_sel_hi:[1,0]
	v_pk_mul_f32 v[86:87], v[228:229], v[84:85] op_sel_hi:[1,0]
	s_waitcnt lgkmcnt(0)
	v_mul_f32_e32 v84, v227, v171
	v_mov_b32_e32 v95, v170
	v_mov_b32_e32 v183, v186
	v_pk_mul_f32 v[90:91], v[238:239], v[90:91]
	v_cndmask_b32_e64 v184, v227, v84, s[6:7]
	v_pk_mul_f32 v[84:85], v[94:95], v[182:183]
	v_mov_b32_e32 v225, v222
	v_mul_f32_e32 v170, v226, v227
	v_pk_mul_f32 v[90:91], v[90:91], v[92:93] op_sel_hi:[1,0]
	v_pk_mul_f32 v[92:93], v[236:237], v[92:93] op_sel_hi:[1,0]
	v_pk_mul_f32 v[84:85], v[84:85], v[184:185] op_sel_hi:[1,0]
	v_pk_mul_f32 v[94:95], v[224:225], v[184:185] op_sel_hi:[1,0]
	v_mul_f32_e32 v173, v170, v171
.LBB0_876:
	v_cvt_pk_bf16_f32 v182, v84, v85
	v_cvt_pk_bf16_f32 v183, v94, v95
	v_cvt_pk_bf16_f32 v184, v88, v89
	v_cvt_pk_bf16_f32 v185, v86, v87
	v_cvt_pk_bf16_f32 v234, v96, v97
	v_cvt_pk_bf16_f32 v235, v98, v99
	v_cvt_pk_bf16_f32 v236, v90, v91
	v_cvt_pk_bf16_f32 v237, v92, v93
	s_nop 0
	v_permlane32_swap_b32_e32 v182, v184
	v_permlane32_swap_b32_e32 v183, v185
	v_permlane32_swap_b32_e32 v234, v236
	v_permlane32_swap_b32_e32 v235, v237
	v_add_u32_e32 v170, s87, v220
	ds_read_b64_tr_b16 v[84:85], v170 offset:0x2000
	ds_read_b64_tr_b16 v[86:87], v170 offset:0x2800
	ds_read_b64_tr_b16 v[88:89], v170 offset:0x3000
	ds_read_b64_tr_b16 v[90:91], v170 offset:0x3800
	s_waitcnt lgkmcnt(0)
	s_nop 0
	v_mfma_f32_32x32x16_bf16 v[52:67], v[182:185], v[84:87], v[52:67]
	ds_read_b64_tr_b16 v[84:85], v170 offset:0x2200
	ds_read_b64_tr_b16 v[86:87], v170 offset:0x2a00
	ds_read_b64_tr_b16 v[92:93], v170 offset:0x3200
	ds_read_b64_tr_b16 v[94:95], v170 offset:0x3a00
	s_waitcnt lgkmcnt(0)
	v_mfma_f32_32x32x16_bf16 v[52:67], v[234:237], v[88:91], v[52:67]
	v_mfma_f32_32x32x16_bf16 v[36:51], v[182:185], v[84:87], v[36:51]
	ds_read_b64_tr_b16 v[84:85], v170 offset:0x2400
	ds_read_b64_tr_b16 v[86:87], v170 offset:0x2c00
	ds_read_b64_tr_b16 v[88:89], v170 offset:0x3400
	ds_read_b64_tr_b16 v[90:91], v170 offset:0x3c00
	s_waitcnt lgkmcnt(0)
	v_mfma_f32_32x32x16_bf16 v[36:51], v[234:237], v[92:95], v[36:51]
	v_mfma_f32_32x32x16_bf16 v[20:35], v[182:185], v[84:87], v[20:35]
	ds_read_b64_tr_b16 v[84:85], v170 offset:0x2600
	ds_read_b64_tr_b16 v[86:87], v170 offset:0x2e00
	ds_read_b64_tr_b16 v[238:239], v170 offset:0x3600
	ds_read_b64_tr_b16 v[240:241], v170 offset:0x3e00
	s_waitcnt lgkmcnt(0)
	v_mfma_f32_32x32x16_bf16 v[20:35], v[234:237], v[88:91], v[20:35]
	v_mfma_f32_32x32x16_bf16 v[4:19], v[182:185], v[84:87], v[4:19]
	ds_read_b128 v[182:185], v172 offset:32768
	ds_read_b128 v[186:189], v174 offset:32768
	s_mov_b64 s[8:9], -1
	s_andn2_b64 vcc, exec, s[50:51]
	s_waitcnt lgkmcnt(1)
	v_mfma_f32_32x32x16_bf16 v[84:99], v[182:185], v[100:103], v[68:83]
	s_waitcnt lgkmcnt(0)
	v_mfma_f32_32x32x16_bf16 v[84:99], v[186:189], v[104:107], v[84:99]
	ds_read_b128 v[182:185], v175 offset:32768
	ds_read_b128 v[186:189], v176 offset:32768
	s_waitcnt lgkmcnt(1)
	v_mfma_f32_32x32x16_bf16 v[84:99], v[182:185], v[108:111], v[84:99]
	ds_read_b128 v[174:177], v177 offset:32768
	ds_read_b128 v[182:185], v178 offset:32768
	s_waitcnt lgkmcnt(2)
	v_mfma_f32_32x32x16_bf16 v[84:99], v[186:189], v[112:115], v[84:99]
	s_waitcnt lgkmcnt(1)
	v_mfma_f32_32x32x16_bf16 v[84:99], v[174:177], v[116:119], v[84:99]
	ds_read_b128 v[174:177], v179 offset:32768
	ds_read_b128 v[222:225], v180 offset:32768
	s_waitcnt lgkmcnt(2)
	v_mfma_f32_32x32x16_bf16 v[84:99], v[182:185], v[120:123], v[84:99]
	s_waitcnt lgkmcnt(1)
	v_mfma_f32_32x32x16_bf16 v[84:99], v[174:177], v[124:127], v[84:99]
	s_waitcnt lgkmcnt(0)
	v_mfma_f32_32x32x16_bf16 v[84:99], v[222:225], v[128:131], v[84:99]
	v_mfma_f32_32x32x16_bf16 v[4:19], v[234:237], v[238:241], v[4:19]
	s_nop 10
	v_max_f32_e64 v232, -v84, -v84
	v_max_f32_e64 v231, -v85, -v85
	v_max_f32_e64 v230, -v86, -v86
	v_max_f32_e64 v229, -v87, -v87
	v_max_f32_e64 v228, -v88, -v88
	v_max_f32_e64 v227, -v89, -v89
	v_max_f32_e64 v226, -v90, -v90
	v_max_f32_e64 v225, -v91, -v91
	v_max_f32_e64 v224, -v92, -v92
	v_max_f32_e64 v223, -v93, -v93
	v_max_f32_e64 v222, -v94, -v94
	v_max_f32_e64 v221, -v95, -v95
	v_max_f32_e64 v94, -v96, -v96
	v_max_f32_e64 v95, -v97, -v97
	v_max_f32_e64 v93, -v98, -v98
	v_max_f32_e64 v92, -v99, -v99
	s_cbranch_vccnz .LBB0_878
; __device__ __forceinline__ float fast_exp2(float x) { return __builtin_amdgcn_exp2f(x); }
; __device__ __forceinline__ float fast_rcp(float x) { return __builtin_amdgcn_rcpf(x); }
; template <int NB, bool MASK> __device__ __forceinline__ void sb_transform(f32x16* P, float& R, int hi, int kpos0, int qpos) {
;     float T[NB][4];
; #pragma unroll
;     for (int b = 0; b < NB; ++b)
; #pragma unroll
;         for (int g = 0; g < 4; ++g) {
;             float be[4], f[4];
; #pragma unroll
;             for (int i = 0; i < 4; ++i) {
;                 const float z = fmaxf(P[b][4 * g + i], -100.f);
;                 const float e = fast_exp2(-z), rc = fast_rcp(1.f + e);
;                 be[i] = rc; f[i] = e * rc;
;                 if (MASK) { const bool ok = (kpos0 + 32 * b + 8 * g + 4 * hi + i) < qpos; be[i] = ok ? be[i] : 0.f; f[i] = ok ? f[i] : 1.f; }
;             }
;             const float e2 = f[3], e1 = f[2] * f[3], e0 = f[1] * e1;
;             T[b][g] = f[0] * e0;
;             P[b][4 * g + 0] = be[0] * e0; P[b][4 * g + 1] = be[1] * e1; P[b][4 * g + 2] = be[2] * e2; P[b][4 * g + 3] = be[3];
;         }
;     float E = R;
; #pragma unroll
;     for (int b = NB - 1; b >= 0; --b)
; #pragma unroll
;         for (int g = 3; g >= 0; --g) {
;             const float To = __shfl_xor(T[b][g], 32);
;             const float Eg = hi ? E : E * To;
; #pragma unroll
;             for (int i = 0; i < 4; ++i) P[b][4 * g + i] *= Eg;
;             E = E * T[b][g] * To;
;         }
;     R = E;
; }
	v_min_f32_e32 v84, 0x42c80000, v232
	v_exp_f32_e32 v84, v84
	v_min_f32_e32 v85, 0x42c80000, v231
	v_exp_f32_e32 v85, v85
	v_min_f32_e32 v91, 0x42c80000, v228
	v_add_f32_e32 v86, 1.0, v84
	v_rcp_f32_e32 v86, v86
	v_add_f32_e32 v87, 1.0, v85
	v_exp_f32_e32 v97, v91
	v_min_f32_e32 v91, 0x42c80000, v227
	v_rcp_f32_e32 v87, v87
	v_exp_f32_e32 v91, v91
	v_min_f32_e32 v90, 0x42c80000, v229
	v_exp_f32_e32 v90, v90
	v_mul_f32_e32 v88, v84, v86
	v_cmp_lt_i32_e32 vcc, v2, v168
	v_or_b32_e32 v89, 1, v2
	v_add_f32_e32 v99, 1.0, v91
	v_cndmask_b32_e32 v84, 0, v86, vcc
	v_cndmask_b32_e32 v86, 1.0, v88, vcc
	v_mul_f32_e32 v88, v85, v87
	v_mov_b32_e32 v85, s45
	v_cmp_lt_i32_e32 vcc, v89, v168
	v_rcp_f32_e32 v171, v99
	v_min_f32_e32 v99, 0x42c80000, v226
	v_cndmask_b32_e32 v85, v85, v87, vcc
	v_min_f32_e32 v87, 0x42c80000, v230
	v_exp_f32_e32 v96, v87
	v_add_f32_e32 v87, 1.0, v90
	v_exp_f32_e32 v172, v99
	v_rcp_f32_e32 v89, v87
	v_add_f32_e32 v87, 1.0, v96
	v_rcp_f32_e32 v98, v87
	v_add_f32_e32 v174, 1.0, v172
	v_mul_f32_e32 v87, v90, v89
	v_or_b32_e32 v90, 3, v2
	v_rcp_f32_e32 v175, v174
	v_min_f32_e32 v174, 0x42c80000, v225
	v_cndmask_b32_e32 v88, 1.0, v88, vcc
	v_cmp_lt_i32_e32 vcc, v90, v168
	v_exp_f32_e32 v174, v174
	v_min_f32_e32 v180, 0x42c80000, v95
	v_cndmask_b32_e32 v90, 1.0, v87, vcc
	v_add_f32_e32 v87, 1.0, v97
	v_rcp_f32_e32 v99, v87
	v_mul_f32_e32 v87, v91, v171
	v_or_b32_e32 v91, 9, v2
	v_cmp_lt_i32_e64 s[8:9], v91, v168
	v_exp_f32_e32 v182, v180
	v_or_b32_e32 v179, 19, v2
	v_cndmask_b32_e64 v91, 1.0, v87, s[8:9]
	v_mul_f32_e32 v87, v172, v175
	v_add_f32_e32 v172, 1.0, v174
	v_rcp_f32_e32 v181, v172
	v_or_b32_e32 v172, 10, v2
	v_cmp_lt_i32_e64 s[10:11], v172, v168
	v_or_b32_e32 v172, 11, v2
	v_cmp_lt_i32_e64 s[12:13], v172, v168
	v_cndmask_b32_e64 v233, 1.0, v87, s[10:11]
	v_mul_f32_e32 v87, v174, v181
	v_min_f32_e32 v174, 0x42c80000, v224
	v_exp_f32_e32 v174, v174
	v_cndmask_b32_e64 v242, 1.0, v87, s[12:13]
	v_min_f32_e32 v87, 0x42c80000, v223
	v_exp_f32_e32 v87, v87
	v_add_f32_e32 v172, 1.0, v174
	v_rcp_f32_e32 v184, v172
	v_or_b32_e32 v172, 16, v2
	v_cmp_lt_i32_e64 s[14:15], v172, v168
	v_min_f32_e32 v172, 0x42c80000, v221
	v_exp_f32_e32 v177, v172
	v_add_f32_e32 v176, 1.0, v87
	v_rcp_f32_e32 v185, v176
	v_min_f32_e32 v176, 0x42c80000, v222
	v_exp_f32_e32 v176, v176
	v_add_f32_e32 v178, 1.0, v177
	v_cmp_lt_i32_e64 s[20:21], v179, v168
	v_add_f32_e32 v179, 1.0, v182
	v_rcp_f32_e32 v186, v178
	v_rcp_f32_e32 v234, v179
	v_min_f32_e32 v179, 0x42c80000, v93
	v_or_b32_e32 v172, 17, v2
	v_exp_f32_e32 v183, v179
	v_mul_f32_e32 v87, v87, v185
	v_cmp_lt_i32_e64 s[16:17], v172, v168
	v_mul_f32_e32 v174, v174, v184
	v_add_f32_e32 v187, 1.0, v183
	v_cndmask_b32_e64 v172, 1.0, v87, s[16:17]
	v_add_f32_e32 v87, 1.0, v176
	v_rcp_f32_e32 v178, v87
	v_mul_f32_e32 v87, v177, v186
	v_min_f32_e32 v177, 0x42c80000, v94
	v_exp_f32_e32 v177, v177
	v_rcp_f32_e32 v238, v187
	v_min_f32_e32 v187, 0x42c80000, v92
	v_exp_f32_e32 v187, v187
	v_cndmask_b32_e64 v180, 1.0, v87, s[20:21]
	v_add_f32_e32 v87, 1.0, v177
	v_rcp_f32_e32 v179, v87
	v_mul_f32_e32 v87, v182, v234
	v_or_b32_e32 v182, 25, v2
	v_cmp_lt_i32_e64 s[26:27], v182, v168
	v_add_f32_e32 v182, 1.0, v187
	v_rcp_f32_e32 v240, v182
	v_or_b32_e32 v182, 26, v2
	v_cndmask_b32_e64 v236, 1.0, v87, s[26:27]
	v_mul_f32_e32 v87, v183, v238
	v_cmp_lt_i32_e64 s[22:23], v182, v168
	v_or_b32_e32 v182, 27, v2
	v_cmp_lt_i32_e64 s[18:19], v182, v168
	v_cndmask_b32_e64 v235, 1.0, v87, s[22:23]
	v_mul_f32_e32 v87, v187, v240
	v_cndmask_b32_e64 v243, 1.0, v87, s[18:19]
	v_xor_b32_e32 v87, 32, v191
	v_add_u32_e32 v182, 64, v192
	v_cmp_lt_i32_e64 s[28:29], v87, v182
	v_or_b32_e32 v182, 18, v2
	v_cmp_lt_i32_e64 s[30:31], v182, v168
	v_cndmask_b32_e64 v87, v191, v87, s[28:29]
	v_lshlrev_b32_e32 v244, 2, v87
	v_or_b32_e32 v87, 24, v2
	v_or_b32_e32 v182, 8, v2
	v_or_b32_e32 v2, 2, v2
	v_pk_mul_f32 v[176:177], v[176:177], v[178:179]
	v_cmp_lt_i32_e64 s[28:29], v87, v1
	v_cmp_lt_i32_e64 s[34:35], v2, v168
	v_mov_b32_e32 v87, s45
	v_mul_f32_e32 v235, v235, v243
	v_cndmask_b32_e64 v177, 1.0, v177, s[28:29]
	v_cndmask_b32_e64 v176, 1.0, v176, s[30:31]
	v_cndmask_b32_e64 v2, 0, v98, s[34:35]
	v_cndmask_b32_e64 v183, v87, v181, s[12:13]
	v_mul_f32_e32 v181, v236, v235
	v_mul_f32_e32 v188, v90, v2
	v_mov_b32_e32 v2, s45
	v_pk_mul_f32 v[236:237], v[176:177], v[180:181]
	v_cndmask_b32_e64 v2, v2, v175, s[10:11]
	v_mov_b32_e32 v175, v237
	v_mov_b32_e32 v255, v237
	s_nop 1
	v_permlane32_swap_b32_e32 v175, v255
	v_cndmask_b32_e64 v175, v175, v255, s[6:7]
	v_cndmask_b32_e32 v189, v87, v89, vcc
	v_cmp_lt_i32_e32 vcc, v182, v1
	v_mul_f32_e32 v182, v242, v2
	v_mov_b32_e32 v2, s45
	v_cndmask_b32_e64 v184, v2, v184, s[14:15]
	v_cndmask_b32_e64 v2, 0, v178, s[30:31]
	v_cndmask_b32_e64 v187, v87, v186, s[20:21]
	v_mul_f32_e32 v186, v180, v2
	v_mov_b32_e32 v2, s45
	v_cndmask_b32_e64 v174, 1.0, v174, s[14:15]
	v_cndmask_b32_e64 v2, v2, v238, s[22:23]
	v_pk_mul_f32 v[238:239], v[172:173], v[236:237]
	v_cndmask_b32_e64 v185, v87, v185, s[16:17]
	s_waitcnt lgkmcnt(0)
	v_pk_mul_f32 v[176:177], v[174:175], v[238:239]
	v_mov_b32_e32 v89, v176
	v_mov_b32_e32 v255, v176
	s_nop 1
	v_permlane32_swap_b32_e32 v89, v255
	v_cndmask_b32_e64 v89, v89, v255, s[6:7]
	v_cndmask_b32_e64 v178, 0, v179, s[28:29]
	v_cndmask_b32_e64 v179, v87, v234, s[26:27]
	v_mov_b32_e32 v234, v181
	v_mov_b32_e32 v239, v236
	v_pk_mul_f32 v[96:97], v[96:97], v[98:99]
	v_cndmask_b32_e64 v241, v87, v240, s[18:19]
	v_mul_f32_e32 v240, v243, v2
	v_mul_f32_e32 v2, v173, v175
	v_pk_mul_f32 v[174:175], v[234:235], v[178:179]
	v_pk_mul_f32 v[178:179], v[238:239], v[184:185]
	v_mul_f32_e32 v185, v233, v242
	v_cndmask_b32_e32 v97, 1.0, v97, vcc
	v_cndmask_b32_e64 v96, 1.0, v96, s[34:35]
	v_cndmask_b32_e32 v98, 0, v99, vcc
	v_cndmask_b32_e64 v99, v87, v171, s[8:9]
	s_waitcnt lgkmcnt(0)
; __device__ __forceinline__ float fast_exp2(float x) { return __builtin_amdgcn_exp2f(x); }
; __device__ __forceinline__ float fast_rcp(float x) { return __builtin_amdgcn_rcpf(x); }
; template <int NB, bool MASK> __device__ __forceinline__ void sb_transform(f32x16* P, float& R, int hi, int kpos0, int qpos) {
;     float T[NB][4];
; #pragma unroll
;     for (int b = 0; b < NB; ++b)
; #pragma unroll
;         for (int g = 0; g < 4; ++g) {
;             float be[4], f[4];
; #pragma unroll
;             for (int i = 0; i < 4; ++i) {
;                 const float z = fmaxf(P[b][4 * g + i], -100.f);
;                 const float e = fast_exp2(-z), rc = fast_rcp(1.f + e);
;                 be[i] = rc; f[i] = e * rc;
;                 if (MASK) { const bool ok = (kpos0 + 32 * b + 8 * g + 4 * hi + i) < qpos; be[i] = ok ? be[i] : 0.f; f[i] = ok ? f[i] : 1.f; }
;             }
;             const float e2 = f[3], e1 = f[2] * f[3], e0 = f[1] * e1;
;             T[b][g] = f[0] * e0;
;             P[b][4 * g + 0] = be[0] * e0; P[b][4 * g + 1] = be[1] * e1; P[b][4 * g + 2] = be[2] * e2; P[b][4 * g + 3] = be[3];
;         }
;     float E = R;
; #pragma unroll
;     for (int b = NB - 1; b >= 0; --b)
; #pragma unroll
;         for (int g = 3; g >= 0; --g) {
;             const float To = __shfl_xor(T[b][g], 32);
;             const float Eg = hi ? E : E * To;
; #pragma unroll
;             for (int i = 0; i < 4; ++i) P[b][4 * g + i] *= Eg;
;             E = E * T[b][g] * To;
;         }
;     R = E;
; }
	v_mul_f32_e32 v87, v177, v89
	v_mul_f32_e32 v91, v91, v185
	v_cndmask_b32_e64 v172, v177, v87, s[6:7]
	v_mul_f32_e32 v87, v176, v177
	v_pk_mul_f32 v[96:97], v[96:97], v[90:91]
	v_mul_f32_e32 v89, v87, v89
	v_mov_b32_e32 v87, v97
	v_mov_b32_e32 v255, v97
	s_nop 1
	v_permlane32_swap_b32_e32 v87, v255
	v_cndmask_b32_e64 v87, v87, v255, s[6:7]
	v_pk_mul_f32 v[180:181], v[186:187], v[172:173] op_sel_hi:[1,0]
	v_pk_mul_f32 v[186:187], v[88:89], v[96:97]
	v_mov_b32_e32 v184, v91
	v_pk_mul_f32 v[90:91], v[184:185], v[98:99]
	s_waitcnt lgkmcnt(0)
	v_pk_mul_f32 v[98:99], v[86:87], v[186:187]
	v_mov_b32_e32 v86, v98
	v_mov_b32_e32 v255, v98
	s_nop 1
	v_permlane32_swap_b32_e32 v86, v255
	v_cndmask_b32_e64 v86, v86, v255, s[6:7]
	v_cndmask_b32_e64 v2, v173, v2, s[6:7]
	v_pk_mul_f32 v[176:177], v[174:175], v[2:3] op_sel_hi:[1,0]
	v_pk_mul_f32 v[174:175], v[240:241], v[2:3] op_sel_hi:[1,0]
	v_mul_f32_e32 v2, v89, v87
	v_cndmask_b32_e64 v2, v89, v2, s[6:7]
	v_pk_mul_f32 v[184:185], v[90:91], v[2:3] op_sel_hi:[1,0]
	v_pk_mul_f32 v[182:183], v[182:183], v[2:3] op_sel_hi:[1,0]
	s_waitcnt lgkmcnt(0)
	v_mul_f32_e32 v2, v99, v86
	v_mov_b32_e32 v187, v96
	v_cndmask_b32_e64 v2, v99, v2, s[6:7]
	v_pk_mul_f32 v[84:85], v[186:187], v[84:85]
	v_pk_mul_f32 v[188:189], v[188:189], v[2:3] op_sel_hi:[1,0]
	v_pk_mul_f32 v[186:187], v[84:85], v[2:3] op_sel_hi:[1,0]
	v_mul_f32_e32 v2, v98, v99
	v_pk_mul_f32 v[178:179], v[178:179], v[172:173] op_sel_hi:[1,0]
	v_mul_f32_e32 v171, v2, v86
	s_mov_b64 s[8:9], 0
.LBB0_878:
	s_andn2_b64 vcc, exec, s[8:9]
	s_cbranch_vccnz .LBB0_880
	v_min_f32_e32 v2, 0x42c80000, v232
	v_exp_f32_e32 v2, v2
	v_min_f32_e32 v84, 0x42c80000, v231
	v_exp_f32_e32 v84, v84
	v_min_f32_e32 v85, 0x42c80000, v230
	v_add_f32_e32 v86, 1.0, v2
	v_rcp_f32_e32 v86, v86
	v_min_f32_e32 v87, 0x42c80000, v229
	v_exp_f32_e32 v88, v85
	v_add_f32_e32 v85, 1.0, v84
	v_exp_f32_e32 v96, v87
	v_rcp_f32_e32 v98, v85
	v_min_f32_e32 v85, 0x42c80000, v228
	v_exp_f32_e32 v89, v85
	v_min_f32_e32 v85, 0x42c80000, v227
	v_exp_f32_e32 v85, v85
	v_min_f32_e32 v87, 0x42c80000, v226
	v_mul_f32_e32 v90, v2, v86
	v_add_f32_e32 v2, 1.0, v88
	v_exp_f32_e32 v174, v87
	v_min_f32_e32 v87, 0x42c80000, v225
	v_rcp_f32_e32 v182, v2
	v_add_f32_e32 v2, 1.0, v96
	v_exp_f32_e32 v175, v87
	v_rcp_f32_e32 v172, v2
	v_add_f32_e32 v2, 1.0, v89
	v_rcp_f32_e32 v183, v2
	v_add_f32_e32 v2, 1.0, v85
	v_rcp_f32_e32 v185, v2
	v_add_f32_e32 v2, 1.0, v174
	v_rcp_f32_e32 v186, v2
	v_add_f32_e32 v2, 1.0, v175
	v_rcp_f32_e32 v187, v2
	v_min_f32_e32 v2, 0x42c80000, v224
	v_exp_f32_e32 v2, v2
	v_mul_f32_e32 v97, v85, v185
	v_pk_mul_f32 v[174:175], v[174:175], v[186:187]
	v_min_f32_e32 v87, 0x42c80000, v222
	v_add_f32_e32 v85, 1.0, v2
	v_rcp_f32_e32 v178, v85
	v_min_f32_e32 v85, 0x42c80000, v223
	v_pk_mul_f32 v[188:189], v[174:175], v[174:175] op_sel:[0,1] op_sel_hi:[1,0]
	v_exp_f32_e32 v174, v87
	v_min_f32_e32 v87, 0x42c80000, v221
	v_exp_f32_e32 v176, v85
	v_mul_f32_e32 v186, v186, v175
	v_exp_f32_e32 v175, v87
	v_min_f32_e32 v87, 0x42c80000, v93
	v_exp_f32_e32 v228, v87
	v_min_f32_e32 v87, 0x42c80000, v92
	v_add_f32_e32 v85, 1.0, v174
	v_mul_f32_e32 v222, v2, v178
	v_add_f32_e32 v2, 1.0, v176
	v_exp_f32_e32 v229, v87
	v_rcp_f32_e32 v180, v85
	v_add_f32_e32 v85, 1.0, v175
	v_rcp_f32_e32 v224, v2
	v_min_f32_e32 v2, 0x42c80000, v95
	v_rcp_f32_e32 v181, v85
	v_exp_f32_e32 v2, v2
	v_min_f32_e32 v85, 0x42c80000, v94
	v_exp_f32_e32 v94, v85
	v_add_f32_e32 v87, 1.0, v228
	v_rcp_f32_e32 v92, v87
	v_add_f32_e32 v87, 1.0, v229
	v_rcp_f32_e32 v93, v87
	v_add_f32_e32 v85, 1.0, v2
	v_rcp_f32_e32 v85, v85
	v_add_f32_e32 v87, 1.0, v94
	v_rcp_f32_e32 v230, v87
	v_pk_mul_f32 v[228:229], v[228:229], v[92:93]
	v_mul_f32_e32 v95, v2, v85
	v_pk_mul_f32 v[232:233], v[228:229], v[228:229] op_sel:[0,1] op_sel_hi:[1,0]
	v_xor_b32_e32 v2, 32, v191
	v_mov_b32_e32 v231, v232
	v_add_u32_e32 v87, 64, v192
	v_pk_mul_f32 v[94:95], v[94:95], v[230:231]
	v_cmp_lt_i32_e32 vcc, v2, v87
	v_mov_b32_e32 v177, v94
	v_mov_b32_e32 v225, v95
	v_cndmask_b32_e32 v2, v191, v2, vcc
	v_lshlrev_b32_e32 v87, 2, v2
	v_pk_mul_f32 v[176:177], v[176:177], v[224:225]
	v_mov_b32_e32 v223, v177
	v_mov_b32_e32 v255, v177
	s_nop 1
	v_permlane32_swap_b32_e32 v223, v255
	v_cndmask_b32_e64 v223, v223, v255, s[6:7]
	v_pk_mul_f32 v[174:175], v[174:175], v[180:181]
	v_mul_f32_e32 v92, v92, v229
	v_pk_mul_f32 v[226:227], v[174:175], v[174:175] op_sel:[0,1] op_sel_hi:[1,0]
	v_mov_b32_e32 v231, v85
	v_mov_b32_e32 v227, v173
	v_pk_mul_f32 v[228:229], v[226:227], v[176:177]
	s_waitcnt lgkmcnt(0)
	v_mul_f32_e32 v2, v173, v223
	v_pk_mul_f32 v[222:223], v[228:229], v[222:223]
	v_mov_b32_e32 v99, v222
	v_mov_b32_e32 v255, v222
	s_nop 1
	v_permlane32_swap_b32_e32 v99, v255
	v_cndmask_b32_e64 v99, v99, v255, s[6:7]
	v_pk_mov_b32 v[94:95], v[94:95], v[232:233] op_sel:[1,0]
	v_cndmask_b32_e64 v2, v173, v2, s[6:7]
	v_pk_mul_f32 v[94:95], v[230:231], v[94:95]
	v_mov_b32_e32 v173, v188
	v_pk_mul_f32 v[176:177], v[94:95], v[2:3] op_sel_hi:[1,0]
	v_pk_mul_f32 v[88:89], v[88:89], v[182:183]
	v_pk_mul_f32 v[94:95], v[96:97], v[172:173]
	v_mul_f32_e32 v180, v180, v175
	v_pk_mul_f32 v[174:175], v[92:93], v[2:3] op_sel_hi:[1,0]
	s_waitcnt lgkmcnt(0)
	v_mul_f32_e32 v2, v223, v99
	v_mov_b32_e32 v179, v224
	v_mov_b32_e32 v229, v226
	v_pk_mul_f32 v[88:89], v[88:89], v[94:95]
	v_cndmask_b32_e64 v2, v223, v2, s[6:7]
	v_pk_mul_f32 v[92:93], v[178:179], v[228:229]
	v_mov_b32_e32 v91, v89
	v_mov_b32_e32 v255, v89
	s_nop 1
	v_permlane32_swap_b32_e32 v91, v255
	v_cndmask_b32_e64 v91, v91, v255, s[6:7]
	v_pk_mul_f32 v[178:179], v[92:93], v[2:3] op_sel_hi:[1,0]
	v_pk_mul_f32 v[92:93], v[222:223], v[222:223] op_sel_hi:[0,1]
	v_mov_b32_e32 v85, v93
	v_pk_mul_f32 v[84:85], v[84:85], v[98:99]
	v_pk_mul_f32 v[180:181], v[180:181], v[2:3] op_sel_hi:[1,0]
	v_pk_mul_f32 v[92:93], v[88:89], v[84:85]
	s_waitcnt lgkmcnt(0)
	v_mul_f32_e32 v2, v85, v91
	v_pk_mul_f32 v[90:91], v[92:93], v[90:91]
	v_mov_b32_e32 v89, v90
	v_mov_b32_e32 v255, v90
	s_nop 1
	v_permlane32_swap_b32_e32 v89, v255
	v_cndmask_b32_e64 v89, v89, v255, s[6:7]
	v_mul_f32_e32 v84, v182, v94
	v_mov_b32_e32 v184, v183
	v_pk_mov_b32 v[94:95], v[94:95], v[188:189] op_sel:[1,0]
	v_cndmask_b32_e64 v2, v85, v2, s[6:7]
	v_pk_mul_f32 v[94:95], v[184:185], v[94:95]
	v_pk_mul_f32 v[182:183], v[186:187], v[2:3] op_sel_hi:[1,0]
	v_pk_mul_f32 v[184:185], v[94:95], v[2:3] op_sel_hi:[1,0]
	s_waitcnt lgkmcnt(0)
	v_mul_f32_e32 v2, v91, v89
	v_mov_b32_e32 v87, v98
	v_mov_b32_e32 v93, v88
	v_cndmask_b32_e64 v2, v91, v2, s[6:7]
	v_pk_mul_f32 v[86:87], v[86:87], v[92:93]
	v_mov_b32_e32 v85, v172
	v_pk_mul_f32 v[186:187], v[86:87], v[2:3] op_sel_hi:[1,0]
	v_pk_mul_f32 v[188:189], v[84:85], v[2:3] op_sel_hi:[1,0]
	v_mul_f32_e32 v2, v90, v91
	v_mul_f32_e32 v171, v2, v89

; #define LAS __attribute__((address_space(3)))
; __global__ void __launch_bounds__(512, 2) hymba_fwd(Params p) {
;     extern __shared__ __attribute__((aligned(16))) unsigned char lds_raw[];
;     LAS unsigned char* lds = (LAS unsigned char*)lds_raw;
	.amdhsa_kernel _Z9hymba_fwd6Params
		.amdhsa_group_segment_fixed_size 0
		.amdhsa_private_segment_fixed_size 0
		.amdhsa_kernarg_size 488
		.amdhsa_user_sgpr_count 2
		.amdhsa_user_sgpr_dispatch_ptr 0
		.amdhsa_user_sgpr_queue_ptr 0
		.amdhsa_user_sgpr_kernarg_segment_ptr 1
		.amdhsa_user_sgpr_dispatch_id 0
		.amdhsa_user_sgpr_kernarg_preload_length 0
		.amdhsa_user_sgpr_kernarg_preload_offset 0
		.amdhsa_user_sgpr_private_segment_size 0
		.amdhsa_uses_dynamic_stack 0
		.amdhsa_enable_private_segment 0
		.amdhsa_system_sgpr_workgroup_id_x 1
		.amdhsa_system_sgpr_workgroup_id_y 0
		.amdhsa_system_sgpr_workgroup_id_z 0
		.amdhsa_system_sgpr_workgroup_info 0
		.amdhsa_system_vgpr_workitem_id 0
		.amdhsa_next_free_vgpr 256
		.amdhsa_next_free_sgpr 102
		.amdhsa_accum_offset 256
		.amdhsa_reserve_vcc 1
		.amdhsa_float_round_mode_32 0
		.amdhsa_float_round_mode_16_64 0
		.amdhsa_float_denorm_mode_32 3
		.amdhsa_float_denorm_mode_16_64 3
		.amdhsa_dx10_clamp 1
		.amdhsa_ieee_mode 1
		.amdhsa_fp16_overflow 0
		.amdhsa_tg_split 0
		.amdhsa_exception_fp_ieee_invalid_op 0
		.amdhsa_exception_fp_denorm_src 0
		.amdhsa_exception_fp_ieee_div_zero 0
		.amdhsa_exception_fp_ieee_overflow 0
		.amdhsa_exception_fp_ieee_underflow 0
		.amdhsa_exception_fp_ieee_inexact 0
		.amdhsa_exception_int_div_zero 0
	.end_amdhsa_kernel

; #define LAS __attribute__((address_space(3)))
; __global__ void __launch_bounds__(512, 2) hymba_fwd(Params p) {
;     extern __shared__ __attribute__((aligned(16))) unsigned char lds_raw[];
;     LAS unsigned char* lds = (LAS unsigned char*)lds_raw;
amdhsa.kernels:
  - .agpr_count:     0
    .args:
      - .offset:         0
        .size:           232
        .value_kind:     by_value
      - .offset:         232
        .size:           4
        .value_kind:     hidden_block_count_x
      - .offset:         236
        .size:           4
        .value_kind:     hidden_block_count_y
      - .offset:         240
        .size:           4
        .value_kind:     hidden_block_count_z
      - .offset:         244
        .size:           2
        .value_kind:     hidden_group_size_x
      - .offset:         246
        .size:           2
        .value_kind:     hidden_group_size_y
      - .offset:         248
        .size:           2
        .value_kind:     hidden_group_size_z
      - .offset:         250
        .size:           2
        .value_kind:     hidden_remainder_x
      - .offset:         252
        .size:           2
        .value_kind:     hidden_remainder_y
      - .offset:         254
        .size:           2
        .value_kind:     hidden_remainder_z
      - .offset:         272
        .size:           8
        .value_kind:     hidden_global_offset_x
      - .offset:         280
        .size:           8
        .value_kind:     hidden_global_offset_y
      - .offset:         288
        .size:           8
        .value_kind:     hidden_global_offset_z
      - .offset:         296
        .size:           2
        .value_kind:     hidden_grid_dims
      - .offset:         352
        .size:           4
        .value_kind:     hidden_dynamic_lds_size
    .group_segment_fixed_size: 0
    .kernarg_segment_align: 8
    .kernarg_segment_size: 488
    .language:       OpenCL C
    .language_version:
      - 2
      - 0
    .max_flat_workgroup_size: 512
    .name:           _Z9hymba_fwd6Params
    .private_segment_fixed_size: 0
    .sgpr_count:     108
    .sgpr_spill_count: 48
    .symbol:         _Z9hymba_fwd6Params.kd
    .uniform_work_group_size: 1
    .uses_dynamic_stack: false
    .vgpr_count:     256
    .vgpr_spill_count: 0
    .wavefront_size: 64
